# attention loop: removed redundant canonicalising v_max ops around the row-max reduction and replaced v_cndmask+v_cmp mask build by one s_andn2 (6 fewer VALU per step pair)
# speedup vs baseline: 1.0858x; 1.0858x over previous
; #define SBAR() __builtin_amdgcn_sched_barrier(0)
; __device__ __forceinline__ unsigned cvtpk(float lo, float hi) { unsigned r; asm volatile("v_cvt_pk_bf16_f32 %0, %1, %2" : "=v"(r) : "v"(lo), "v"(hi)); return r; }
; __device__ __forceinline__ void qkt_fin(f32x16& n0, f32x16& n1, const bf16_t* Ks, const bf16x8* qr, const f32x16& negm, int r32, int hi, ...
;   float psa = 0.f, psb = 0.f; u32x4 wa, wb, wc, wd;
;     ...
; #pragma unroll
;   for (int d0 = 0; d0 < 8; ++d0) { int cb = (d0 * 16 + hi * 8) * 2;
;     bf16x8 b0 = *reinterpret_cast<const bf16x8*>((const char*)Ks + KSWZ(r32, cb));
;     bf16x8 b1 = *reinterpret_cast<const bf16x8*>((const char*)Ks + KSWZ(32 + r32, cb));
;     SBAR(); if (d0 == 0) n0 = __builtin_amdgcn_mfma_f32_32x32x16_bf16(b0, qr[0], negm, 0, 0, 0); else n0 = __builtin_amdgcn_mfma_f32_32x32x16_bf16(b0, qr[d0], n0, 0, 0, 0);
;     SBAR(); QF_CHUNK(2 * d0); SBAR();
;     if (d0 == 0) n1 = __builtin_amdgcn_mfma_f32_32x32x16_bf16(b1, qr[0], negm, 0, 0, 0); else n1 = __builtin_amdgcn_mfma_f32_32x32x16_bf16(b1, qr[d0], n1, 0, 0, 0);
;     SBAR(); QF_CHUNK(2 * d0 + 1); SBAR();
;     if (d0 == 7) { vf8_read<0>(vf0, vbv); SBAR(); } }
;     ...
;   psb += P1[15]; wd[3] = cvtpk(P1[14], P1[15]);
;   l_reg = l_reg * alpha + (psa + psb);
;   pa0 = *reinterpret_cast<bf16x8*>(&wa); pa1 = *reinterpret_cast<bf16x8*>(&wb); pa2 = *reinterpret_cast<bf16x8*>(&wc); pa3 = *reinterpret_cast<bf16x8*>(&wd);
; }
.LBB0_453:
	s_add_i32 s97, s96, 0xffff8000
	s_xor_b32 s98, s96, 0x10000
	s_add_i32 s99, s96, 0x8000
	s_and_b32 s99, s99, 0x18000
	v_add_u32_e32 v196, s96, v236
	ds_read_b128 v[98:101], v196 offset:16384
	ds_read_b128 v[196:199], v196 offset:24576
	v_add_u32_e32 v252, s96, v237
	ds_read_b128 v[248:251], v252 offset:16384
	ds_read_b128 v[252:255], v252 offset:24576
	v_add_u32_e32 v0, s97, v235
	s_waitcnt lgkmcnt(3)
	v_mfma_f32_32x32x16_bf16 v[132:147], v[98:101], v[152:155], v[66:81]
	v_exp_f32_e32 v82, v82
	s_waitcnt lgkmcnt(2)
	v_mfma_f32_32x32x16_bf16 v[98:113], v[196:199], v[152:155], v[66:81]
	v_exp_f32_e32 v83, v83
	v_add_f32_e32 v245, v115, v114
	v_cvt_pk_bf16_f32 v196, v114, v115
	v_add_u32_e32 v206, s96, v238
	ds_read_b128 v[202:205], v206 offset:16384
	ds_read_b128 v[206:209], v206 offset:24576
	s_waitcnt lgkmcnt(3)
	v_mfma_f32_32x32x16_bf16 v[132:147], v[248:251], v[160:163], v[132:147]
	v_exp_f32_e32 v84, v84
	v_add_f32_e32 v245, v116, v245
	v_add_f32_e32 v246, v82, v83
	s_waitcnt lgkmcnt(2)
	v_mfma_f32_32x32x16_bf16 v[98:113], v[252:255], v[160:163], v[98:113]
	v_exp_f32_e32 v85, v85
	v_add_f32_e32 v245, v117, v245
	v_add_f32_e32 v246, v246, v84
	v_cvt_pk_bf16_f32 v197, v116, v117
	v_cvt_pk_bf16_f32 v200, v82, v83
	v_add_u32_e32 v252, s96, v239
	ds_read_b128 v[248:251], v252 offset:16384
	ds_read_b128 v[252:255], v252 offset:24576
	s_waitcnt lgkmcnt(3)
	v_mfma_f32_32x32x16_bf16 v[132:147], v[202:205], v[148:151], v[132:147]
	v_exp_f32_e32 v86, v86
	v_add_f32_e32 v245, v118, v245
	v_add_f32_e32 v246, v246, v85
	s_waitcnt lgkmcnt(2)
	v_mfma_f32_32x32x16_bf16 v[98:113], v[206:209], v[148:151], v[98:113]
	v_exp_f32_e32 v87, v87
	v_add_f32_e32 v245, v119, v245
	v_add_f32_e32 v246, v246, v86
	v_cvt_pk_bf16_f32 v198, v118, v119
	v_cvt_pk_bf16_f32 v201, v84, v85
	v_add_u32_e32 v208, s96, v240
	ds_read_b128 v[204:207], v208 offset:16384
	ds_read_b128 v[208:211], v208 offset:24576
	s_waitcnt lgkmcnt(3)
	v_mfma_f32_32x32x16_bf16 v[132:147], v[248:251], v[156:159], v[132:147]
	v_exp_f32_e32 v88, v88
	v_add_f32_e32 v245, v120, v245
	v_add_f32_e32 v246, v246, v87
	s_waitcnt lgkmcnt(2)
	v_mfma_f32_32x32x16_bf16 v[98:113], v[252:255], v[156:159], v[98:113]
	v_exp_f32_e32 v89, v89
	v_add_f32_e32 v245, v121, v245
	v_add_f32_e32 v246, v246, v88
	v_cvt_pk_bf16_f32 v199, v120, v121
	v_cvt_pk_bf16_f32 v202, v86, v87
	v_add_u32_e32 v252, s96, v241
	ds_read_b128 v[248:251], v252 offset:16384
	ds_read_b128 v[252:255], v252 offset:24576
	s_waitcnt lgkmcnt(3)
	v_mfma_f32_32x32x16_bf16 v[132:147], v[204:207], v[168:171], v[132:147]
	v_exp_f32_e32 v90, v90
	v_add_f32_e32 v245, v122, v245
	v_add_f32_e32 v246, v246, v89
	s_waitcnt lgkmcnt(2)
	v_mfma_f32_32x32x16_bf16 v[98:113], v[208:211], v[168:171], v[98:113]
	v_exp_f32_e32 v91, v91
	v_add_f32_e32 v245, v123, v245
	v_add_f32_e32 v246, v246, v90
	v_cvt_pk_bf16_f32 v204, v122, v123
	v_cvt_pk_bf16_f32 v203, v88, v89
	v_add_u32_e32 v118, s96, v242
	ds_read_b128 v[114:117], v118 offset:16384
	ds_read_b128 v[118:121], v118 offset:24576
	s_waitcnt lgkmcnt(3)
	v_mfma_f32_32x32x16_bf16 v[132:147], v[248:251], v[176:179], v[132:147]
	v_exp_f32_e32 v92, v92
	v_add_f32_e32 v245, v124, v245
	v_add_f32_e32 v246, v246, v91
	s_waitcnt lgkmcnt(2)
	v_mfma_f32_32x32x16_bf16 v[98:113], v[252:255], v[176:179], v[98:113]
	v_exp_f32_e32 v93, v93
	v_add_f32_e32 v245, v125, v245
	v_add_f32_e32 v246, v246, v92
	v_cvt_pk_bf16_f32 v205, v124, v125
	v_cvt_pk_bf16_f32 v208, v90, v91
	v_add_u32_e32 v252, s96, v243
	ds_read_b128 v[248:251], v252 offset:16384
	ds_read_b128 v[252:255], v252 offset:24576
	s_waitcnt lgkmcnt(3)
	v_mfma_f32_32x32x16_bf16 v[132:147], v[114:117], v[164:167], v[132:147]
	v_exp_f32_e32 v94, v94
	v_add_f32_e32 v245, v126, v245
	v_add_f32_e32 v246, v246, v93
	s_waitcnt lgkmcnt(2)
	v_mfma_f32_32x32x16_bf16 v[98:113], v[118:121], v[164:167], v[98:113]
	v_exp_f32_e32 v95, v95
	v_add_f32_e32 v245, v127, v245
	v_add_f32_e32 v246, v246, v94
	v_cvt_pk_bf16_f32 v206, v126, v127
	v_cvt_pk_bf16_f32 v209, v92, v93
	s_waitcnt lgkmcnt(1)
	v_mfma_f32_32x32x16_bf16 v[132:147], v[248:251], v[172:175], v[132:147]
	v_exp_f32_e32 v96, v96
	v_add_f32_e32 v245, v128, v245
	v_add_f32_e32 v246, v246, v95
	s_waitcnt lgkmcnt(0)
	v_mfma_f32_32x32x16_bf16 v[98:113], v[252:255], v[172:175], v[98:113]
	v_exp_f32_e32 v97, v97
	v_add_f32_e32 v245, v129, v245
	v_add_f32_e32 v246, v246, v96
	v_cvt_pk_bf16_f32 v207, v128, v129
	v_cvt_pk_bf16_f32 v210, v94, v95
	v_mov_b32_e32 v131, v97
	v_cvt_pk_bf16_f32 v211, v96, v97
	ds_read_b64_tr_b16 v[94:95], v0 offset:0
	ds_read_b64_tr_b16 v[96:97], v0 offset:2048
	ds_read_b64_tr_b16 v[90:91], v0 offset:4096
	ds_read_b64_tr_b16 v[92:93], v0 offset:6144
	ds_read_b64_tr_b16 v[86:87], v0 offset:8192
	ds_read_b64_tr_b16 v[88:89], v0 offset:10240
	ds_read_b64_tr_b16 v[82:83], v0 offset:12288
	ds_read_b64_tr_b16 v[84:85], v0 offset:14336
	s_andn2_b64 s[8:9], exec, s[0:1]
	s_andn2_b64 vcc, exec, s[0:1]
	s_cbranch_vccnz .LBB0_456
; template <bool FIRST, bool DOEXP = true>
; __device__ __forceinline__ void partialSM(f32x16& p0, f32x16& p1, float& m_reg, f32x16& negm, float& alpha, const bool track = true) {
;     ...
;   float pmax = p0[0];
; #pragma unroll
;   for (int r = 1; r < 16; ++r) pmax = fmaxf(pmax, p0[r]);
; #pragma unroll
;   for (int r = 0; r < 16; ++r) pmax = fmaxf(pmax, p1[r]);
;   { auto rr = __builtin_amdgcn_permlane32_swap(__float_as_uint(pmax), __float_as_uint(pmax), false, false);
;     pmax = fmaxf(__uint_as_float(rr[0]), __uint_as_float(rr[1])); }
;   if (!FIRST && __builtin_expect(__all(pmax <= THRL), 1)) { alpha = 1.f; }
;   else { const float dl = FIRST ? pmax : fmaxf(pmax, 0.f); m_reg += dl; alpha = FIRST ? 1.f : __builtin_amdgcn_exp2f(-dl);
; #pragma unroll
;     for (int r = 0; r < 16; ++r) { p0[r] -= dl; p1[r] -= dl; }
; #pragma unroll
;     for (int r = 0; r < 16; ++r) negm[r] = -m_reg;
;     asm volatile("" : "+v"(negm)); }
	v_max_f32_e32 v114, v132, v133
	v_max3_f32 v114, v114, v134, v135
	v_max3_f32 v114, v114, v136, v137
	v_max3_f32 v114, v114, v138, v139
	v_max3_f32 v114, v114, v140, v141
	v_max3_f32 v114, v114, v142, v143
	v_max3_f32 v114, v114, v144, v145
	v_max3_f32 v114, v114, v146, v147
	v_max3_f32 v114, v114, v98, v99
	v_max3_f32 v114, v114, v100, v101
	v_max3_f32 v114, v114, v102, v103
	v_max3_f32 v114, v114, v104, v105
	v_max3_f32 v114, v114, v106, v107
	v_max3_f32 v114, v114, v108, v109
	v_max3_f32 v114, v114, v110, v111
	v_max3_f32 v114, v114, v112, v113
	v_mov_b32_e32 v115, v114
	s_nop 1
	v_permlane32_swap_b32_e32 v114, v115
	v_max_f32_e32 v114, v114, v115
	v_cmp_ge_f32_e32 vcc, s69, v114
	s_cmp_eq_u64 vcc, exec
	v_mov_b32_e32 v130, 1.0
	s_cbranch_scc1 .LBB0_457
	v_max_f32_e32 v66, v114, v114
	v_max_f32_e32 v66, 0, v66
	v_exp_f32_e64 v130, -v66
	v_add_f32_e32 v222, v222, v66
	v_sub_f32_e32 v147, v147, v66
	v_sub_f32_e32 v146, v146, v66
	v_sub_f32_e32 v145, v145, v66
	v_sub_f32_e32 v144, v144, v66
	v_sub_f32_e32 v143, v143, v66
	v_sub_f32_e32 v142, v142, v66
	v_sub_f32_e32 v141, v141, v66
	v_sub_f32_e32 v140, v140, v66
	v_sub_f32_e32 v139, v139, v66
	v_sub_f32_e32 v138, v138, v66
	v_sub_f32_e32 v137, v137, v66
	v_sub_f32_e32 v136, v136, v66
	v_sub_f32_e32 v135, v135, v66
	v_sub_f32_e32 v134, v134, v66
	v_sub_f32_e32 v133, v133, v66
	v_sub_f32_e32 v132, v132, v66
	v_sub_f32_e32 v113, v113, v66
	v_sub_f32_e32 v112, v112, v66
	v_sub_f32_e32 v111, v111, v66
	v_sub_f32_e32 v110, v110, v66
	v_sub_f32_e32 v109, v109, v66
	v_sub_f32_e32 v108, v108, v66
	v_sub_f32_e32 v107, v107, v66
	v_sub_f32_e32 v106, v106, v66
	v_sub_f32_e32 v105, v105, v66
	v_sub_f32_e32 v104, v104, v66
	v_sub_f32_e32 v103, v103, v66
	v_sub_f32_e32 v102, v102, v66
	v_sub_f32_e32 v101, v101, v66
	v_sub_f32_e32 v100, v100, v66
	v_sub_f32_e32 v99, v99, v66
	v_sub_f32_e32 v98, v98, v66
	v_xor_b32_e32 v66, 0x80000000, v222
	v_mov_b32_e32 v67, v66
	v_mov_b32_e32 v68, v66
	v_mov_b32_e32 v69, v66
	v_mov_b32_e32 v70, v66
	v_mov_b32_e32 v71, v66
	v_mov_b32_e32 v72, v66
	v_mov_b32_e32 v73, v66
	v_mov_b32_e32 v74, v66
	v_mov_b32_e32 v75, v66
	v_mov_b32_e32 v76, v66
	v_mov_b32_e32 v77, v66
	v_mov_b32_e32 v78, v66
	v_mov_b32_e32 v79, v66
	v_mov_b32_e32 v80, v66
	v_mov_b32_e32 v81, v66
	s_branch .LBB0_457

; #define SBAR() __builtin_amdgcn_sched_barrier(0)
; __device__ __forceinline__ unsigned cvtpk(float lo, float hi) { unsigned r; asm volatile("v_cvt_pk_bf16_f32 %0, %1, %2" : "=v"(r) : "v"(lo), "v"(hi)); return r; }
; template <bool FIRST, bool DOEXP = true>
; __device__ __forceinline__ void partialSM(f32x16& p0, f32x16& p1, float& m_reg, f32x16& negm, float& alpha, const bool track = true) {
;     ...
;   float pmax = p0[0];
; #pragma unroll
;   for (int r = 1; r < 16; ++r) pmax = fmaxf(pmax, p0[r]);
; #pragma unroll
;   for (int r = 0; r < 16; ++r) pmax = fmaxf(pmax, p1[r]);
;   { auto rr = __builtin_amdgcn_permlane32_swap(__float_as_uint(pmax), __float_as_uint(pmax), false, false);
;     pmax = fmaxf(__uint_as_float(rr[0]), __uint_as_float(rr[1])); }
; __device__ __forceinline__ void qkt_fin(f32x16& n0, f32x16& n1, const bf16_t* Ks, const bf16x8* qr, const f32x16& negm, int r32, int hi, ...
;   float psa = 0.f, psb = 0.f; u32x4 wa, wb, wc, wd;
;     ...
; #pragma unroll
;   for (int d0 = 0; d0 < 8; ++d0) { int cb = (d0 * 16 + hi * 8) * 2;
;     bf16x8 b0 = *reinterpret_cast<const bf16x8*>((const char*)Ks + KSWZ(r32, cb));
;     bf16x8 b1 = *reinterpret_cast<const bf16x8*>((const char*)Ks + KSWZ(32 + r32, cb));
;     SBAR(); if (d0 == 0) n0 = __builtin_amdgcn_mfma_f32_32x32x16_bf16(b0, qr[0], negm, 0, 0, 0); else n0 = __builtin_amdgcn_mfma_f32_32x32x16_bf16(b0, qr[d0], n0, 0, 0, 0);
;     SBAR(); QF_CHUNK(2 * d0); SBAR();
;     if (d0 == 0) n1 = __builtin_amdgcn_mfma_f32_32x32x16_bf16(b1, qr[0], negm, 0, 0, 0); else n1 = __builtin_amdgcn_mfma_f32_32x32x16_bf16(b1, qr[d0], n1, 0, 0, 0);
;     SBAR(); QF_CHUNK(2 * d0 + 1); SBAR();
;     if (d0 == 7) { vf8_read<0>(vf0, vbv); SBAR(); } }
;     ...
;   psb += P1[15]; wd[3] = cvtpk(P1[14], P1[15]);
;   l_reg = l_reg * alpha + (psa + psb);
;   pa0 = *reinterpret_cast<bf16x8*>(&wa); pa1 = *reinterpret_cast<bf16x8*>(&wb); pa2 = *reinterpret_cast<bf16x8*>(&wc); pa3 = *reinterpret_cast<bf16x8*>(&wd);
; }
.LBB0_461:
	s_waitcnt lgkmcnt(0)
	v_add_u32_e32 v208, s99, v236
	ds_read_b128 v[204:207], v208 offset:16384
	ds_read_b128 v[208:211], v208 offset:24576
	v_add_u32_e32 v252, s99, v237
	ds_read_b128 v[248:251], v252 offset:16384
	ds_read_b128 v[252:255], v252 offset:24576
	v_add_u32_e32 v203, s96, v235
	s_waitcnt lgkmcnt(3)
	v_mfma_f32_32x32x16_bf16 v[114:129], v[204:207], v[152:155], v[66:81]
	v_exp_f32_e32 v98, v98
	s_waitcnt lgkmcnt(2)
	v_mfma_f32_32x32x16_bf16 v[82:97], v[208:211], v[152:155], v[66:81]
	v_exp_f32_e32 v99, v99
	v_add_f32_e32 v201, v133, v132
	v_cvt_pk_bf16_f32 v132, v132, v133
	v_add_u32_e32 v208, s99, v238
	ds_read_b128 v[204:207], v208 offset:16384
	ds_read_b128 v[208:211], v208 offset:24576
	s_waitcnt lgkmcnt(3)
	v_mfma_f32_32x32x16_bf16 v[114:129], v[248:251], v[160:163], v[114:129]
	v_exp_f32_e32 v100, v100
	v_add_f32_e32 v201, v134, v201
	v_add_f32_e32 v202, v98, v99
	s_waitcnt lgkmcnt(2)
	v_mfma_f32_32x32x16_bf16 v[82:97], v[252:255], v[160:163], v[82:97]
	v_exp_f32_e32 v101, v101
	v_add_f32_e32 v201, v135, v201
	v_add_f32_e32 v202, v202, v100
	v_cvt_pk_bf16_f32 v133, v134, v135
	v_cvt_pk_bf16_f32 v196, v98, v99
	v_add_u32_e32 v252, s99, v239
	ds_read_b128 v[248:251], v252 offset:16384
	ds_read_b128 v[252:255], v252 offset:24576
	s_waitcnt lgkmcnt(3)
	v_mfma_f32_32x32x16_bf16 v[114:129], v[204:207], v[148:151], v[114:129]
	v_exp_f32_e32 v102, v102
	v_add_f32_e32 v201, v136, v201
	v_add_f32_e32 v202, v202, v101
	s_waitcnt lgkmcnt(2)
	v_mfma_f32_32x32x16_bf16 v[82:97], v[208:211], v[148:151], v[82:97]
	v_exp_f32_e32 v103, v103
	v_add_f32_e32 v201, v137, v201
	v_add_f32_e32 v202, v202, v102
	v_cvt_pk_bf16_f32 v134, v136, v137
	v_cvt_pk_bf16_f32 v197, v100, v101
	v_add_u32_e32 v208, s99, v240
	ds_read_b128 v[204:207], v208 offset:16384
	ds_read_b128 v[208:211], v208 offset:24576
	s_waitcnt lgkmcnt(3)
	v_mfma_f32_32x32x16_bf16 v[114:129], v[248:251], v[156:159], v[114:129]
	v_exp_f32_e32 v104, v104
	v_add_f32_e32 v201, v138, v201
	v_add_f32_e32 v202, v202, v103
	s_waitcnt lgkmcnt(2)
	v_mfma_f32_32x32x16_bf16 v[82:97], v[252:255], v[156:159], v[82:97]
	v_exp_f32_e32 v105, v105
	v_add_f32_e32 v201, v139, v201
	v_add_f32_e32 v202, v202, v104
	v_cvt_pk_bf16_f32 v135, v138, v139
	v_cvt_pk_bf16_f32 v198, v102, v103
	v_add_u32_e32 v252, s99, v241
	ds_read_b128 v[248:251], v252 offset:16384
	ds_read_b128 v[252:255], v252 offset:24576
	s_waitcnt lgkmcnt(3)
	v_mfma_f32_32x32x16_bf16 v[114:129], v[204:207], v[168:171], v[114:129]
	v_exp_f32_e32 v106, v106
	v_add_f32_e32 v201, v140, v201
	v_add_f32_e32 v202, v202, v105
	s_waitcnt lgkmcnt(2)
	v_mfma_f32_32x32x16_bf16 v[82:97], v[208:211], v[168:171], v[82:97]
	v_exp_f32_e32 v107, v107
	v_add_f32_e32 v201, v141, v201
	v_add_f32_e32 v202, v202, v106
	v_cvt_pk_bf16_f32 v136, v140, v141
	v_cvt_pk_bf16_f32 v199, v104, v105
	v_add_u32_e32 v208, s99, v242
	ds_read_b128 v[204:207], v208 offset:16384
	ds_read_b128 v[208:211], v208 offset:24576
	s_waitcnt lgkmcnt(3)
	v_mfma_f32_32x32x16_bf16 v[114:129], v[248:251], v[176:179], v[114:129]
	v_exp_f32_e32 v108, v108
	v_add_f32_e32 v201, v142, v201
	v_add_f32_e32 v202, v202, v107
	s_waitcnt lgkmcnt(2)
	v_mfma_f32_32x32x16_bf16 v[82:97], v[252:255], v[176:179], v[82:97]
	v_exp_f32_e32 v109, v109
	v_add_f32_e32 v201, v143, v201
	v_add_f32_e32 v202, v202, v108
	v_cvt_pk_bf16_f32 v137, v142, v143
	v_cvt_pk_bf16_f32 v140, v106, v107
	v_add_u32_e32 v252, s99, v243
	ds_read_b128 v[248:251], v252 offset:16384
	ds_read_b128 v[252:255], v252 offset:24576
	s_waitcnt lgkmcnt(3)
	v_mfma_f32_32x32x16_bf16 v[114:129], v[204:207], v[164:167], v[114:129]
	v_exp_f32_e32 v110, v110
	v_add_f32_e32 v201, v144, v201
	v_add_f32_e32 v202, v202, v109
	s_waitcnt lgkmcnt(2)
	v_mfma_f32_32x32x16_bf16 v[82:97], v[208:211], v[164:167], v[82:97]
	v_exp_f32_e32 v111, v111
	v_add_f32_e32 v201, v145, v201
	v_add_f32_e32 v202, v202, v110
	v_cvt_pk_bf16_f32 v138, v144, v145
	v_cvt_pk_bf16_f32 v141, v108, v109
	s_waitcnt lgkmcnt(1)
	v_mfma_f32_32x32x16_bf16 v[114:129], v[248:251], v[172:175], v[114:129]
	v_exp_f32_e32 v112, v112
	v_add_f32_e32 v201, v146, v201
	v_add_f32_e32 v202, v202, v111
	s_waitcnt lgkmcnt(0)
	v_mfma_f32_32x32x16_bf16 v[82:97], v[252:255], v[172:175], v[82:97]
	v_exp_f32_e32 v113, v113
	v_add_f32_e32 v201, v147, v201
	v_add_f32_e32 v202, v202, v112
	v_cvt_pk_bf16_f32 v139, v146, v147
	v_cvt_pk_bf16_f32 v142, v110, v111
	ds_read_b64_tr_b16 v[144:145], v203 offset:0
	ds_read_b64_tr_b16 v[146:147], v203 offset:2048
	s_nop 0
	ds_read_b64_tr_b16 v[106:107], v203 offset:4096
	ds_read_b64_tr_b16 v[108:109], v203 offset:6144
	ds_read_b64_tr_b16 v[102:103], v203 offset:8192
	ds_read_b64_tr_b16 v[104:105], v203 offset:10240
	ds_read_b64_tr_b16 v[98:99], v203 offset:12288
	ds_read_b64_tr_b16 v[100:101], v203 offset:14336
	v_cvt_pk_bf16_f32 v143, v112, v113
	s_and_b64 vcc, exec, s[8:9]
	v_mov_b32_e32 v200, 1.0
	s_cbranch_vccnz .LBB0_463
	v_max_f32_e32 v110, v114, v115
	v_max3_f32 v110, v110, v116, v117
	v_max3_f32 v110, v110, v118, v119
	v_max3_f32 v110, v110, v120, v121
	v_max3_f32 v110, v110, v122, v123
	v_max3_f32 v110, v110, v124, v125
	v_max3_f32 v110, v110, v126, v127
	v_max3_f32 v110, v110, v128, v129
	v_max3_f32 v110, v110, v82, v83
	v_max3_f32 v110, v110, v84, v85
	v_max3_f32 v110, v110, v86, v87
	v_max3_f32 v110, v110, v88, v89
	v_max3_f32 v110, v110, v90, v91
	v_max3_f32 v110, v110, v92, v93
	v_max3_f32 v110, v110, v94, v95
	v_max3_f32 v110, v110, v96, v97
	v_mov_b32_e32 v111, v110
	s_nop 1
	v_permlane32_swap_b32_e32 v110, v111
	v_max_f32_e32 v110, v110, v111
	v_cmp_ge_f32_e32 vcc, s69, v110
	s_cmp_eq_u64 vcc, exec
	v_mov_b32_e32 v200, 1.0
	s_cbranch_scc0 .LBB0_469

; #define SBAR() __builtin_amdgcn_sched_barrier(0)
; __device__ __forceinline__ unsigned cvtpk(float lo, float hi) { unsigned r; asm volatile("v_cvt_pk_bf16_f32 %0, %1, %2" : "=v"(r) : "v"(lo), "v"(hi)); return r; }
; __device__ __forceinline__ void qkt_fin(f32x16& n0, f32x16& n1, const bf16_t* Ks, const bf16x8* qr, const f32x16& negm, int r32, int hi, ...
;   float psa = 0.f, psb = 0.f; u32x4 wa, wb, wc, wd;
;     ...
; #pragma unroll
;   for (int d0 = 0; d0 < 8; ++d0) { int cb = (d0 * 16 + hi * 8) * 2;
;     bf16x8 b0 = *reinterpret_cast<const bf16x8*>((const char*)Ks + KSWZ(r32, cb));
;     bf16x8 b1 = *reinterpret_cast<const bf16x8*>((const char*)Ks + KSWZ(32 + r32, cb));
;     SBAR(); if (d0 == 0) n0 = __builtin_amdgcn_mfma_f32_32x32x16_bf16(b0, qr[0], negm, 0, 0, 0); else n0 = __builtin_amdgcn_mfma_f32_32x32x16_bf16(b0, qr[d0], n0, 0, 0, 0);
;     SBAR(); QF_CHUNK(2 * d0); SBAR();
;     if (d0 == 0) n1 = __builtin_amdgcn_mfma_f32_32x32x16_bf16(b1, qr[0], negm, 0, 0, 0); else n1 = __builtin_amdgcn_mfma_f32_32x32x16_bf16(b1, qr[d0], n1, 0, 0, 0);
;     SBAR(); QF_CHUNK(2 * d0 + 1); SBAR();
;     if (d0 == 7) { vf8_read<0>(vf0, vbv); SBAR(); } }
;     ...
;   psb += P1[15]; wd[3] = cvtpk(P1[14], P1[15]);
;   l_reg = l_reg * alpha + (psa + psb);
;   pa0 = *reinterpret_cast<bf16x8*>(&wa); pa1 = *reinterpret_cast<bf16x8*>(&wb); pa2 = *reinterpret_cast<bf16x8*>(&wc); pa3 = *reinterpret_cast<bf16x8*>(&wd);
; }
.Lh2_453:
	s_setprio 1
	s_add_i32 s97, s96, 0xffff8000
	s_xor_b32 s98, s96, 0x10000
	s_add_i32 s99, s96, 0x8000
	s_and_b32 s99, s99, 0x18000
	v_add_u32_e32 v196, s96, v236
	ds_read_b128 v[98:101], v196 offset:16384
	ds_read_b128 v[196:199], v196 offset:24576
	v_add_u32_e32 v252, s96, v237
	ds_read_b128 v[248:251], v252 offset:16384
	ds_read_b128 v[252:255], v252 offset:24576
	v_add_u32_e32 v0, s97, v235
	s_waitcnt lgkmcnt(3)
	v_mfma_f32_32x32x16_bf16 v[132:147], v[98:101], v[152:155], v[66:81]
	v_exp_f32_e32 v82, v82
	s_waitcnt lgkmcnt(2)
	v_mfma_f32_32x32x16_bf16 v[98:113], v[196:199], v[152:155], v[66:81]
	v_exp_f32_e32 v83, v83
	v_add_f32_e32 v245, v115, v114
	v_cvt_pk_bf16_f32 v196, v114, v115
	v_add_u32_e32 v206, s96, v238
	ds_read_b128 v[202:205], v206 offset:16384
	ds_read_b128 v[206:209], v206 offset:24576
	s_waitcnt lgkmcnt(3)
	v_mfma_f32_32x32x16_bf16 v[132:147], v[248:251], v[160:163], v[132:147]
	v_exp_f32_e32 v84, v84
	v_add_f32_e32 v245, v116, v245
	v_add_f32_e32 v246, v82, v83
	s_waitcnt lgkmcnt(2)
	v_mfma_f32_32x32x16_bf16 v[98:113], v[252:255], v[160:163], v[98:113]
	v_exp_f32_e32 v85, v85
	v_add_f32_e32 v245, v117, v245
	v_add_f32_e32 v246, v246, v84
	v_cvt_pk_bf16_f32 v197, v116, v117
	v_cvt_pk_bf16_f32 v200, v82, v83
	v_add_u32_e32 v252, s96, v239
	ds_read_b128 v[248:251], v252 offset:16384
	ds_read_b128 v[252:255], v252 offset:24576
	s_add_i32 s79, s99, s100
	s_add_i32 m0, s79, 0x4000
	s_add_i32 s79, s79, 0x6000
	global_load_lds_dwordx4 v[180:181], off
	s_waitcnt lgkmcnt(3)
	v_mfma_f32_32x32x16_bf16 v[132:147], v[202:205], v[148:151], v[132:147]
	v_exp_f32_e32 v86, v86
	v_add_f32_e32 v245, v118, v245
	v_add_f32_e32 v246, v246, v85
	s_waitcnt lgkmcnt(2)
	v_mfma_f32_32x32x16_bf16 v[98:113], v[206:209], v[148:151], v[98:113]
	v_exp_f32_e32 v87, v87
	v_add_f32_e32 v245, v119, v245
	v_add_f32_e32 v246, v246, v86
	v_cvt_pk_bf16_f32 v198, v118, v119
	v_cvt_pk_bf16_f32 v201, v84, v85
	v_add_u32_e32 v208, s96, v240
	ds_read_b128 v[204:207], v208 offset:16384
	ds_read_b128 v[208:211], v208 offset:24576
	s_mov_b32 m0, s79
	s_add_i32 s79, s99, s101
	global_load_lds_dwordx4 v[182:183], off
	s_waitcnt lgkmcnt(3)
	v_mfma_f32_32x32x16_bf16 v[132:147], v[248:251], v[156:159], v[132:147]
	v_exp_f32_e32 v88, v88
	v_add_f32_e32 v245, v120, v245
	v_add_f32_e32 v246, v246, v87
	s_waitcnt lgkmcnt(2)
	v_mfma_f32_32x32x16_bf16 v[98:113], v[252:255], v[156:159], v[98:113]
	v_exp_f32_e32 v89, v89
	v_add_f32_e32 v245, v121, v245
	v_add_f32_e32 v246, v246, v88
	v_cvt_pk_bf16_f32 v199, v120, v121
	v_cvt_pk_bf16_f32 v202, v86, v87
	v_add_u32_e32 v252, s96, v241
	ds_read_b128 v[248:251], v252 offset:16384
	ds_read_b128 v[252:255], v252 offset:24576
	s_mov_b32 m0, s79
	s_add_i32 s79, s79, 0x380
	global_load_lds_dwordx4 v[214:215], off
	s_waitcnt lgkmcnt(3)
	v_mfma_f32_32x32x16_bf16 v[132:147], v[204:207], v[168:171], v[132:147]
	v_exp_f32_e32 v90, v90
	v_add_f32_e32 v245, v122, v245
	v_add_f32_e32 v246, v246, v89
	s_waitcnt lgkmcnt(2)
	v_mfma_f32_32x32x16_bf16 v[98:113], v[208:211], v[168:171], v[98:113]
	v_exp_f32_e32 v91, v91
	v_add_f32_e32 v245, v123, v245
	v_add_f32_e32 v246, v246, v90
	v_cvt_pk_bf16_f32 v204, v122, v123
	v_cvt_pk_bf16_f32 v203, v88, v89
	v_add_u32_e32 v118, s96, v242
	ds_read_b128 v[114:117], v118 offset:16384
	ds_read_b128 v[118:121], v118 offset:24576
	s_mov_b32 m0, s79
	s_nop 0
	global_load_lds_dwordx4 v[214:215], off offset:128
	v_lshl_add_u64 v[180:181], v[180:181], 0, s[76:77]
	v_lshl_add_u64 v[182:183], v[182:183], 0, s[76:77]
	v_lshl_add_u64 v[214:215], v[214:215], 0, s[76:77]
	s_waitcnt lgkmcnt(3)
	v_mfma_f32_32x32x16_bf16 v[132:147], v[248:251], v[176:179], v[132:147]
	v_exp_f32_e32 v92, v92
	v_add_f32_e32 v245, v124, v245
	v_add_f32_e32 v246, v246, v91
	s_waitcnt lgkmcnt(2)
	v_mfma_f32_32x32x16_bf16 v[98:113], v[252:255], v[176:179], v[98:113]
	v_exp_f32_e32 v93, v93
	v_add_f32_e32 v245, v125, v245
	v_add_f32_e32 v246, v246, v92
	v_cvt_pk_bf16_f32 v205, v124, v125
	v_cvt_pk_bf16_f32 v208, v90, v91
	v_add_u32_e32 v252, s96, v243
	ds_read_b128 v[248:251], v252 offset:16384
	ds_read_b128 v[252:255], v252 offset:24576
	s_waitcnt lgkmcnt(3)
	v_mfma_f32_32x32x16_bf16 v[132:147], v[114:117], v[164:167], v[132:147]
	v_exp_f32_e32 v94, v94
	v_add_f32_e32 v245, v126, v245
	v_add_f32_e32 v246, v246, v93
	s_waitcnt lgkmcnt(2)
	v_mfma_f32_32x32x16_bf16 v[98:113], v[118:121], v[164:167], v[98:113]
	v_exp_f32_e32 v95, v95
	v_add_f32_e32 v245, v127, v245
	v_add_f32_e32 v246, v246, v94
	v_cvt_pk_bf16_f32 v206, v126, v127
	v_cvt_pk_bf16_f32 v209, v92, v93
	s_waitcnt lgkmcnt(1)
	v_mfma_f32_32x32x16_bf16 v[132:147], v[248:251], v[172:175], v[132:147]
	v_exp_f32_e32 v96, v96
	v_add_f32_e32 v245, v128, v245
	v_add_f32_e32 v246, v246, v95
	s_waitcnt lgkmcnt(0)
	v_mfma_f32_32x32x16_bf16 v[98:113], v[252:255], v[172:175], v[98:113]
	v_exp_f32_e32 v97, v97
	v_add_f32_e32 v245, v129, v245
	v_add_f32_e32 v246, v246, v96
	v_cvt_pk_bf16_f32 v207, v128, v129
	v_cvt_pk_bf16_f32 v210, v94, v95
	v_mov_b32_e32 v131, v97
	v_cvt_pk_bf16_f32 v211, v96, v97
	ds_read_b64_tr_b16 v[94:95], v0 offset:0
	ds_read_b64_tr_b16 v[96:97], v0 offset:2048
	ds_read_b64_tr_b16 v[90:91], v0 offset:4096
	ds_read_b64_tr_b16 v[92:93], v0 offset:6144
	ds_read_b64_tr_b16 v[86:87], v0 offset:8192
	ds_read_b64_tr_b16 v[88:89], v0 offset:10240
	ds_read_b64_tr_b16 v[82:83], v0 offset:12288
	ds_read_b64_tr_b16 v[84:85], v0 offset:14336
	s_andn2_b64 s[8:9], exec, s[0:1]
	s_andn2_b64 vcc, exec, s[0:1]
	s_cbranch_vccnz .Lh2_456
; template <bool FIRST, bool DOEXP = true>
; __device__ __forceinline__ void partialSM(f32x16& p0, f32x16& p1, float& m_reg, f32x16& negm, float& alpha, const bool track = true) {
;     ...
;   float pmax = p0[0];
; #pragma unroll
;   for (int r = 1; r < 16; ++r) pmax = fmaxf(pmax, p0[r]);
; #pragma unroll
;   for (int r = 0; r < 16; ++r) pmax = fmaxf(pmax, p1[r]);
;   { auto rr = __builtin_amdgcn_permlane32_swap(__float_as_uint(pmax), __float_as_uint(pmax), false, false);
;     pmax = fmaxf(__uint_as_float(rr[0]), __uint_as_float(rr[1])); }
;   if (!FIRST && __builtin_expect(__all(pmax <= THRL), 1)) { alpha = 1.f; }
;   else { const float dl = FIRST ? pmax : fmaxf(pmax, 0.f); m_reg += dl; alpha = FIRST ? 1.f : __builtin_amdgcn_exp2f(-dl);
; #pragma unroll
;     for (int r = 0; r < 16; ++r) { p0[r] -= dl; p1[r] -= dl; }
; #pragma unroll
;     for (int r = 0; r < 16; ++r) negm[r] = -m_reg;
;     asm volatile("" : "+v"(negm)); }
	v_max_f32_e32 v114, v132, v133
	v_max3_f32 v114, v114, v134, v135
	v_max3_f32 v114, v114, v136, v137
	v_max3_f32 v114, v114, v138, v139
	v_max3_f32 v114, v114, v140, v141
	v_max3_f32 v114, v114, v142, v143
	v_max3_f32 v114, v114, v144, v145
	v_max3_f32 v114, v114, v146, v147
	v_max3_f32 v114, v114, v98, v99
	v_max3_f32 v114, v114, v100, v101
	v_max3_f32 v114, v114, v102, v103
	v_max3_f32 v114, v114, v104, v105
	v_max3_f32 v114, v114, v106, v107
	v_max3_f32 v114, v114, v108, v109
	v_max3_f32 v114, v114, v110, v111
	v_max3_f32 v114, v114, v112, v113
	v_mov_b32_e32 v115, v114
	s_nop 1
	v_permlane32_swap_b32_e32 v114, v115
	v_max_f32_e32 v114, v114, v115
	v_cmp_ge_f32_e32 vcc, s69, v114
	s_cmp_eq_u64 vcc, exec
	v_mov_b32_e32 v130, 1.0
	s_cbranch_scc1 .Lh2_457
	v_max_f32_e32 v66, v114, v114
	v_max_f32_e32 v66, 0, v66
	v_exp_f32_e64 v130, -v66
	v_add_f32_e32 v222, v222, v66
	v_sub_f32_e32 v147, v147, v66
	v_sub_f32_e32 v146, v146, v66
	v_sub_f32_e32 v145, v145, v66
	v_sub_f32_e32 v144, v144, v66
	v_sub_f32_e32 v143, v143, v66
	v_sub_f32_e32 v142, v142, v66
	v_sub_f32_e32 v141, v141, v66
	v_sub_f32_e32 v140, v140, v66
	v_sub_f32_e32 v139, v139, v66
	v_sub_f32_e32 v138, v138, v66
	v_sub_f32_e32 v137, v137, v66
	v_sub_f32_e32 v136, v136, v66
	v_sub_f32_e32 v135, v135, v66
	v_sub_f32_e32 v134, v134, v66
	v_sub_f32_e32 v133, v133, v66
	v_sub_f32_e32 v132, v132, v66
	v_sub_f32_e32 v113, v113, v66
	v_sub_f32_e32 v112, v112, v66
	v_sub_f32_e32 v111, v111, v66
	v_sub_f32_e32 v110, v110, v66
	v_sub_f32_e32 v109, v109, v66
	v_sub_f32_e32 v108, v108, v66
	v_sub_f32_e32 v107, v107, v66
	v_sub_f32_e32 v106, v106, v66
	v_sub_f32_e32 v105, v105, v66
	v_sub_f32_e32 v104, v104, v66
	v_sub_f32_e32 v103, v103, v66
	v_sub_f32_e32 v102, v102, v66
	v_sub_f32_e32 v101, v101, v66
	v_sub_f32_e32 v100, v100, v66
	v_sub_f32_e32 v99, v99, v66
	v_sub_f32_e32 v98, v98, v66
	v_xor_b32_e32 v66, 0x80000000, v222
	v_mov_b32_e32 v67, v66
	v_mov_b32_e32 v68, v66
	v_mov_b32_e32 v69, v66
	v_mov_b32_e32 v70, v66
	v_mov_b32_e32 v71, v66
	v_mov_b32_e32 v72, v66
	v_mov_b32_e32 v73, v66
	v_mov_b32_e32 v74, v66
	v_mov_b32_e32 v75, v66
	v_mov_b32_e32 v76, v66
	v_mov_b32_e32 v77, v66
	v_mov_b32_e32 v78, v66
	v_mov_b32_e32 v79, v66
	v_mov_b32_e32 v80, v66
	v_mov_b32_e32 v81, v66
	s_branch .Lh2_457

; #define SBAR() __builtin_amdgcn_sched_barrier(0)
; __device__ __forceinline__ unsigned cvtpk(float lo, float hi) { unsigned r; asm volatile("v_cvt_pk_bf16_f32 %0, %1, %2" : "=v"(r) : "v"(lo), "v"(hi)); return r; }
; template <bool FIRST, bool DOEXP = true>
; __device__ __forceinline__ void partialSM(f32x16& p0, f32x16& p1, float& m_reg, f32x16& negm, float& alpha, const bool track = true) {
;     ...
;   float pmax = p0[0];
; #pragma unroll
;   for (int r = 1; r < 16; ++r) pmax = fmaxf(pmax, p0[r]);
; #pragma unroll
;   for (int r = 0; r < 16; ++r) pmax = fmaxf(pmax, p1[r]);
;   { auto rr = __builtin_amdgcn_permlane32_swap(__float_as_uint(pmax), __float_as_uint(pmax), false, false);
;     pmax = fmaxf(__uint_as_float(rr[0]), __uint_as_float(rr[1])); }
; __device__ __forceinline__ void qkt_fin(f32x16& n0, f32x16& n1, const bf16_t* Ks, const bf16x8* qr, const f32x16& negm, int r32, int hi, ...
;   float psa = 0.f, psb = 0.f; u32x4 wa, wb, wc, wd;
;     ...
; #pragma unroll
;   for (int d0 = 0; d0 < 8; ++d0) { int cb = (d0 * 16 + hi * 8) * 2;
;     bf16x8 b0 = *reinterpret_cast<const bf16x8*>((const char*)Ks + KSWZ(r32, cb));
;     bf16x8 b1 = *reinterpret_cast<const bf16x8*>((const char*)Ks + KSWZ(32 + r32, cb));
;     SBAR(); if (d0 == 0) n0 = __builtin_amdgcn_mfma_f32_32x32x16_bf16(b0, qr[0], negm, 0, 0, 0); else n0 = __builtin_amdgcn_mfma_f32_32x32x16_bf16(b0, qr[d0], n0, 0, 0, 0);
;     SBAR(); QF_CHUNK(2 * d0); SBAR();
;     if (d0 == 0) n1 = __builtin_amdgcn_mfma_f32_32x32x16_bf16(b1, qr[0], negm, 0, 0, 0); else n1 = __builtin_amdgcn_mfma_f32_32x32x16_bf16(b1, qr[d0], n1, 0, 0, 0);
;     SBAR(); QF_CHUNK(2 * d0 + 1); SBAR();
;     if (d0 == 7) { vf8_read<0>(vf0, vbv); SBAR(); } }
;     ...
;   psb += P1[15]; wd[3] = cvtpk(P1[14], P1[15]);
;   l_reg = l_reg * alpha + (psa + psb);
;   pa0 = *reinterpret_cast<bf16x8*>(&wa); pa1 = *reinterpret_cast<bf16x8*>(&wb); pa2 = *reinterpret_cast<bf16x8*>(&wc); pa3 = *reinterpret_cast<bf16x8*>(&wd);
; }
.Lh2_461:
	s_setprio 1
	s_waitcnt lgkmcnt(0)
	s_waitcnt vmcnt(0)
	s_barrier
	v_add_u32_e32 v208, s99, v236
	ds_read_b128 v[204:207], v208 offset:16384
	ds_read_b128 v[208:211], v208 offset:24576
	v_add_u32_e32 v252, s99, v237
	ds_read_b128 v[248:251], v252 offset:16384
	ds_read_b128 v[252:255], v252 offset:24576
	v_add_u32_e32 v203, s96, v235
	s_waitcnt lgkmcnt(3)
	v_mfma_f32_32x32x16_bf16 v[114:129], v[204:207], v[152:155], v[66:81]
	v_exp_f32_e32 v98, v98
	s_waitcnt lgkmcnt(2)
	v_mfma_f32_32x32x16_bf16 v[82:97], v[208:211], v[152:155], v[66:81]
	v_exp_f32_e32 v99, v99
	v_add_f32_e32 v201, v133, v132
	v_cvt_pk_bf16_f32 v132, v132, v133
	v_add_u32_e32 v208, s99, v238
	ds_read_b128 v[204:207], v208 offset:16384
	ds_read_b128 v[208:211], v208 offset:24576
	s_waitcnt lgkmcnt(3)
	v_mfma_f32_32x32x16_bf16 v[114:129], v[248:251], v[160:163], v[114:129]
	v_exp_f32_e32 v100, v100
	v_add_f32_e32 v201, v134, v201
	v_add_f32_e32 v202, v98, v99
	s_waitcnt lgkmcnt(2)
	v_mfma_f32_32x32x16_bf16 v[82:97], v[252:255], v[160:163], v[82:97]
	v_exp_f32_e32 v101, v101
	v_add_f32_e32 v201, v135, v201
	v_add_f32_e32 v202, v202, v100
	v_cvt_pk_bf16_f32 v133, v134, v135
	v_cvt_pk_bf16_f32 v196, v98, v99
	v_add_u32_e32 v252, s99, v239
	ds_read_b128 v[248:251], v252 offset:16384
	ds_read_b128 v[252:255], v252 offset:24576
	s_add_i32 s79, s98, s100
	s_add_i32 m0, s79, 0x4000
	s_add_i32 s79, s79, 0x6000
	global_load_lds_dwordx4 v[180:181], off
	s_waitcnt lgkmcnt(3)
	v_mfma_f32_32x32x16_bf16 v[114:129], v[204:207], v[148:151], v[114:129]
	v_exp_f32_e32 v102, v102
	v_add_f32_e32 v201, v136, v201
	v_add_f32_e32 v202, v202, v101
	s_waitcnt lgkmcnt(2)
	v_mfma_f32_32x32x16_bf16 v[82:97], v[208:211], v[148:151], v[82:97]
	v_exp_f32_e32 v103, v103
	v_add_f32_e32 v201, v137, v201
	v_add_f32_e32 v202, v202, v102
	v_cvt_pk_bf16_f32 v134, v136, v137
	v_cvt_pk_bf16_f32 v197, v100, v101
	v_add_u32_e32 v208, s99, v240
	ds_read_b128 v[204:207], v208 offset:16384
	ds_read_b128 v[208:211], v208 offset:24576
	s_mov_b32 m0, s79
	s_add_i32 s79, s98, s101
	global_load_lds_dwordx4 v[182:183], off
	s_waitcnt lgkmcnt(3)
	v_mfma_f32_32x32x16_bf16 v[114:129], v[248:251], v[156:159], v[114:129]
	v_exp_f32_e32 v104, v104
	v_add_f32_e32 v201, v138, v201
	v_add_f32_e32 v202, v202, v103
	s_waitcnt lgkmcnt(2)
	v_mfma_f32_32x32x16_bf16 v[82:97], v[252:255], v[156:159], v[82:97]
	v_exp_f32_e32 v105, v105
	v_add_f32_e32 v201, v139, v201
	v_add_f32_e32 v202, v202, v104
	v_cvt_pk_bf16_f32 v135, v138, v139
	v_cvt_pk_bf16_f32 v198, v102, v103
	v_add_u32_e32 v252, s99, v241
	ds_read_b128 v[248:251], v252 offset:16384
	ds_read_b128 v[252:255], v252 offset:24576
	s_mov_b32 m0, s79
	s_add_i32 s79, s79, 0x380
	global_load_lds_dwordx4 v[214:215], off
	s_waitcnt lgkmcnt(3)
	v_mfma_f32_32x32x16_bf16 v[114:129], v[204:207], v[168:171], v[114:129]
	v_exp_f32_e32 v106, v106
	v_add_f32_e32 v201, v140, v201
	v_add_f32_e32 v202, v202, v105
	s_waitcnt lgkmcnt(2)
	v_mfma_f32_32x32x16_bf16 v[82:97], v[208:211], v[168:171], v[82:97]
	v_exp_f32_e32 v107, v107
	v_add_f32_e32 v201, v141, v201
	v_add_f32_e32 v202, v202, v106
	v_cvt_pk_bf16_f32 v136, v140, v141
	v_cvt_pk_bf16_f32 v199, v104, v105
	v_add_u32_e32 v208, s99, v242
	ds_read_b128 v[204:207], v208 offset:16384
	ds_read_b128 v[208:211], v208 offset:24576
	s_mov_b32 m0, s79
	s_nop 0
	global_load_lds_dwordx4 v[214:215], off offset:128
	v_lshl_add_u64 v[180:181], v[180:181], 0, s[76:77]
	v_lshl_add_u64 v[182:183], v[182:183], 0, s[76:77]
	v_lshl_add_u64 v[214:215], v[214:215], 0, s[76:77]
	s_waitcnt lgkmcnt(3)
	v_mfma_f32_32x32x16_bf16 v[114:129], v[248:251], v[176:179], v[114:129]
	v_exp_f32_e32 v108, v108
	v_add_f32_e32 v201, v142, v201
	v_add_f32_e32 v202, v202, v107
	s_waitcnt lgkmcnt(2)
	v_mfma_f32_32x32x16_bf16 v[82:97], v[252:255], v[176:179], v[82:97]
	v_exp_f32_e32 v109, v109
	v_add_f32_e32 v201, v143, v201
	v_add_f32_e32 v202, v202, v108
	v_cvt_pk_bf16_f32 v137, v142, v143
	v_cvt_pk_bf16_f32 v140, v106, v107
	v_add_u32_e32 v252, s99, v243
	ds_read_b128 v[248:251], v252 offset:16384
	ds_read_b128 v[252:255], v252 offset:24576
	s_waitcnt lgkmcnt(3)
	v_mfma_f32_32x32x16_bf16 v[114:129], v[204:207], v[164:167], v[114:129]
	v_exp_f32_e32 v110, v110
	v_add_f32_e32 v201, v144, v201
	v_add_f32_e32 v202, v202, v109
	s_waitcnt lgkmcnt(2)
	v_mfma_f32_32x32x16_bf16 v[82:97], v[208:211], v[164:167], v[82:97]
	v_exp_f32_e32 v111, v111
	v_add_f32_e32 v201, v145, v201
	v_add_f32_e32 v202, v202, v110
	v_cvt_pk_bf16_f32 v138, v144, v145
	v_cvt_pk_bf16_f32 v141, v108, v109
	s_waitcnt lgkmcnt(1)
	v_mfma_f32_32x32x16_bf16 v[114:129], v[248:251], v[172:175], v[114:129]
	v_exp_f32_e32 v112, v112
	v_add_f32_e32 v201, v146, v201
	v_add_f32_e32 v202, v202, v111
	s_waitcnt lgkmcnt(0)
	v_mfma_f32_32x32x16_bf16 v[82:97], v[252:255], v[172:175], v[82:97]
	v_exp_f32_e32 v113, v113
	v_add_f32_e32 v201, v147, v201
	v_add_f32_e32 v202, v202, v112
	v_cvt_pk_bf16_f32 v139, v146, v147
	v_cvt_pk_bf16_f32 v142, v110, v111
	ds_read_b64_tr_b16 v[144:145], v203 offset:0
	ds_read_b64_tr_b16 v[146:147], v203 offset:2048
	s_nop 0
	ds_read_b64_tr_b16 v[106:107], v203 offset:4096
	ds_read_b64_tr_b16 v[108:109], v203 offset:6144
	ds_read_b64_tr_b16 v[102:103], v203 offset:8192
	ds_read_b64_tr_b16 v[104:105], v203 offset:10240
	ds_read_b64_tr_b16 v[98:99], v203 offset:12288
	ds_read_b64_tr_b16 v[100:101], v203 offset:14336
	v_cvt_pk_bf16_f32 v143, v112, v113
	s_and_b64 vcc, exec, s[8:9]
	v_mov_b32_e32 v200, 1.0
	s_cbranch_vccnz .Lh2_463
	v_max_f32_e32 v110, v114, v115
	v_max3_f32 v110, v110, v116, v117
	v_max3_f32 v110, v110, v118, v119
	v_max3_f32 v110, v110, v120, v121
	v_max3_f32 v110, v110, v122, v123
	v_max3_f32 v110, v110, v124, v125
	v_max3_f32 v110, v110, v126, v127
	v_max3_f32 v110, v110, v128, v129
	v_max3_f32 v110, v110, v82, v83
	v_max3_f32 v110, v110, v84, v85
	v_max3_f32 v110, v110, v86, v87
	v_max3_f32 v110, v110, v88, v89
	v_max3_f32 v110, v110, v90, v91
	v_max3_f32 v110, v110, v92, v93
	v_max3_f32 v110, v110, v94, v95
	v_max3_f32 v110, v110, v96, v97
	v_mov_b32_e32 v111, v110
	s_nop 1
	v_permlane32_swap_b32_e32 v110, v111
	v_max_f32_e32 v110, v110, v111
	v_cmp_ge_f32_e32 vcc, s69, v110
	s_cmp_eq_u64 vcc, exec
	v_mov_b32_e32 v200, 1.0
	s_cbranch_scc0 .Lh2_469
